# E38 EpiIn q/k gain branch: first gain pair also resident, seven reload pairs removed (on top of E37)
# baseline (speedup 1.0000x reference)
;     __device__ __forceinline__ void operator()(const Acc& acc, const Unit& u, int wr, int wc, int fr, int fq) const {
;     ...
;             if (pn < 4) {
;                 const float* g = (pn < 2) ? qg : kg; bf16_t* dst = (pn < 2) ? Q : Kb;
;                 const float post = (pn < 2) ? 0.125f * LOG2E : 1.0f;
;                 const int head = 4 * (pn & 1) + wc;
; #pragma unroll
;                 for (int ai = 0; ai < 2; ++ai)
; #pragma unroll
;                     for (int m = 0; m < 4; ++m) {
;                         const int row = u.pm * 256 + ai * 128 + wr * 64 + m * 16 + fr;
;                         const float rs = rsv[ai][m];
;                         f32x4 v[2][2]; float ss = 0.f;
; #pragma unroll
;                         for (int bj = 0; bj < 2; ++bj)
; #pragma unroll
;                             for (int n = 0; n < 2; ++n) { v[bj][n] = acc[ai][bj][m][n] * rs; const f32x4 x = v[bj][n]; ss += (x[0] * x[0] + x[1] * x[1]) + (x[2] * x[2] + x[3] * x[3]); }
;                         ss += xshfl<16>(ss); ss += xshfl<32>(ss);
;                         const float hn = __builtin_amdgcn_rsqf(ss * (1.f / 64.f) + EPS) * post;
; #pragma unroll
;                         for (int bj = 0; bj < 2; ++bj) {
;                             float o[8];
; #pragma unroll
;                             for (int n = 0; n < 2; ++n) { const f32x4 gv = *(const f32x4*)(g + 32 * bj + 8 * fq + 4 * n);
; #pragma unroll
;                                 for (int j = 0; j < 4; ++j) o[4 * n + j] = v[bj][n][j] * hn * gv[j]; }
;                             st16(dst + (size_t)row * 512 + head * 64 + 32 * bj + 8 * fq, o);
;                         }
;                         asm volatile("" ::: "memory");
;                     }
.LBB0_207:
	s_andn2_b64 vcc, exec, s[0:1]
	s_cbranch_vccnz .LBB0_209
	s_cmp_lt_i32 s60, 2
	s_cselect_b64 vcc, -1, 0
	s_and_b64 s[0:1], vcc, exec
	s_mov_b32 s0, 0x6000000
	s_cselect_b32 s34, s0, 0x7000000
	s_cselect_b32 s0, s43, s47
	s_cselect_b32 s1, s42, s46
	s_add_u32 s0, s0, s18
	s_addc_u32 s1, s1, s19
	v_lshlrev_b32_e32 v171, 2, v136
	global_load_dwordx4 v[186:189], v171, s[0:1]
	global_load_dwordx4 v[190:193], v171, s[0:1] offset:16
	global_load_dwordx4 v[216:219], v171, s[0:1] offset:128
	global_load_dwordx4 v[220:223], v171, s[0:1] offset:144
	global_load_dwordx4 v[224:227], v171, s[0:1]
	global_load_dwordx4 v[228:231], v171, s[0:1] offset:16
	v_pk_mul_f32 v[122:123], v[184:185], v[122:123] op_sel_hi:[0,1]
	v_pk_mul_f32 v[120:121], v[184:185], v[120:121] op_sel_hi:[0,1]
	v_pk_mul_f32 v[126:127], v[184:185], v[126:127] op_sel_hi:[0,1]
	v_pk_mul_f32 v[124:125], v[184:185], v[124:125] op_sel_hi:[0,1]
	v_pk_mul_f32 v[194:195], v[184:185], v[118:119] op_sel_hi:[0,1]
	v_pk_mul_f32 v[196:197], v[184:185], v[116:117] op_sel_hi:[0,1]
	v_pk_mul_f32 v[198:199], v[184:185], v[114:115] op_sel_hi:[0,1]
	v_pk_mul_f32 v[184:185], v[184:185], v[112:113] op_sel_hi:[0,1]
	v_add_u32_e32 v112, s23, v139
	v_pk_mul_f32 v[114:115], v[122:123], v[122:123]
	v_pk_mul_f32 v[116:117], v[120:121], v[120:121]
	v_pk_mul_f32 v[118:119], v[126:127], v[126:127]
	v_pk_mul_f32 v[200:201], v[124:125], v[124:125]
	v_mul_f32_e32 v202, v196, v196
	v_mul_f32_e32 v204, v194, v194
	v_ashrrev_i32_e32 v113, 31, v112
	v_pk_mov_b32 v[206:207], v[116:117], v[114:115] op_sel:[1,0]
	v_mov_b32_e32 v117, v115
	v_pk_mov_b32 v[114:115], v[200:201], v[118:119] op_sel:[1,0]
	v_mov_b32_e32 v201, v119
	v_pk_fma_f32 v[118:119], v[196:197], v[196:197], v[202:203] op_sel_hi:[1,1,0]
	v_pk_fma_f32 v[202:203], v[194:195], v[194:195], v[204:205] op_sel_hi:[1,1,0]
	v_lshlrev_b64 v[204:205], 10, v[112:113]
	v_pk_add_f32 v[112:113], v[206:207], v[116:117]
	v_pk_add_f32 v[114:115], v[114:115], v[200:201]
	v_pk_add_f32 v[112:113], v[112:113], v[112:113] op_sel_hi:[0,1]
	v_pk_add_f32 v[114:115], v[114:115], v[114:115] op_sel_hi:[0,1]
	v_mul_f32_e32 v118, v184, v184
	v_mul_f32_e32 v202, v185, v185
	v_mul_f32_e32 v112, v198, v198
	v_mul_f32_e32 v114, v199, v199
	v_pk_add_f32 v[116:117], v[118:119], v[202:203]
	v_pk_add_f32 v[112:113], v[112:113], v[114:115]
	v_mov_b32_e32 v156, 0x3e38aa3b
	v_pk_add_f32 v[112:113], v[116:117], v[112:113]
	v_cndmask_b32_e32 v173, 1.0, v156, vcc
	v_add_f32_e32 v112, v112, v113
	ds_swizzle_b32 v113, v112 offset:swizzle(SWAP,16)
	v_cmp_eq_u32_e32 vcc, 0, v214
	s_add_u32 s30, s30, s34
	s_addc_u32 s31, s31, 0
	s_lshl_b32 s34, s60, 2
	s_waitcnt lgkmcnt(0)
	v_add_f32_e32 v112, v112, v113
	v_mov_b32_e32 v113, v112
	v_mov_b32_e32 v114, v112
	s_nop 1
	v_permlane32_swap_b32_e32 v113, v114
	v_cndmask_b32_e32 v113, v113, v114, vcc
	v_add_f32_e32 v112, v112, v113
	s_and_b32 s34, s34, 4
	v_fmamk_f32 v112, v112, 0x3c800000, v212
	s_or_b32 s34, s34, s88
	v_rsq_f32_e32 v114, v112
	s_lshl_b32 s34, s34, 7
	s_add_u32 s30, s30, s34
	v_lshlrev_b32_e32 v156, 1, v136
	s_addc_u32 s31, s31, 0
	v_lshl_add_u64 v[112:113], s[30:31], 0, v[156:157]
	v_mul_f32_e32 v156, v173, v114
	v_pk_mul_f32 v[114:115], v[120:121], v[156:157] op_sel_hi:[1,0]
	v_pk_mul_f32 v[116:117], v[122:123], v[156:157] op_sel_hi:[1,0]
	v_pk_mul_f32 v[118:119], v[124:125], v[156:157] op_sel_hi:[1,0]
	v_pk_mul_f32 v[120:121], v[126:127], v[156:157] op_sel_hi:[1,0]
	v_lshl_add_u64 v[200:201], v[112:113], 0, v[204:205]
	v_pk_mul_f32 v[122:123], v[196:197], v[156:157] op_sel_hi:[1,0]
	v_pk_mul_f32 v[124:125], v[194:195], v[156:157] op_sel_hi:[1,0]
	v_pk_mul_f32 v[126:127], v[184:185], v[156:157] op_sel_hi:[1,0]
	v_pk_mul_f32 v[184:185], v[198:199], v[156:157] op_sel_hi:[1,0]
	v_pk_mul_f32 v[110:111], v[182:183], v[110:111] op_sel_hi:[0,1]
	v_pk_mul_f32 v[108:109], v[182:183], v[108:109] op_sel_hi:[0,1]
	v_pk_mul_f32 v[106:107], v[182:183], v[106:107] op_sel_hi:[0,1]
	v_pk_mul_f32 v[104:105], v[182:183], v[104:105] op_sel_hi:[0,1]
	v_pk_mul_f32 v[94:95], v[180:181], v[94:95] op_sel_hi:[0,1]
	v_pk_mul_f32 v[92:93], v[180:181], v[92:93] op_sel_hi:[0,1]
	v_pk_mul_f32 v[90:91], v[180:181], v[90:91] op_sel_hi:[0,1]
	v_pk_mul_f32 v[88:89], v[180:181], v[88:89] op_sel_hi:[0,1]
	v_pk_mul_f32 v[78:79], v[178:179], v[78:79] op_sel_hi:[0,1]
	v_pk_mul_f32 v[76:77], v[178:179], v[76:77] op_sel_hi:[0,1]
	s_waitcnt vmcnt(1)
	v_pk_mul_f32 v[114:115], v[186:187], v[114:115]
	v_pk_mul_f32 v[116:117], v[188:189], v[116:117]
	s_waitcnt vmcnt(0)
;     __device__ __forceinline__ void operator()(const Acc& acc, const Unit& u, int wr, int wc, int fr, int fq) const {
;     ...
;             if (pn < 4) {
;                 const float* g = (pn < 2) ? qg : kg; bf16_t* dst = (pn < 2) ? Q : Kb;
;                 const float post = (pn < 2) ? 0.125f * LOG2E : 1.0f;
;                 const int head = 4 * (pn & 1) + wc;
; #pragma unroll
;                 for (int ai = 0; ai < 2; ++ai)
; #pragma unroll
;                     for (int m = 0; m < 4; ++m) {
;                         const int row = u.pm * 256 + ai * 128 + wr * 64 + m * 16 + fr;
;                         const float rs = rsv[ai][m];
;                         f32x4 v[2][2]; float ss = 0.f;
; #pragma unroll
;                         for (int bj = 0; bj < 2; ++bj)
; #pragma unroll
;                             for (int n = 0; n < 2; ++n) { v[bj][n] = acc[ai][bj][m][n] * rs; const f32x4 x = v[bj][n]; ss += (x[0] * x[0] + x[1] * x[1]) + (x[2] * x[2] + x[3] * x[3]); }
;                         ss += xshfl<16>(ss); ss += xshfl<32>(ss);
;                         const float hn = __builtin_amdgcn_rsqf(ss * (1.f / 64.f) + EPS) * post;
; #pragma unroll
;                         for (int bj = 0; bj < 2; ++bj) {
;                             float o[8];
; #pragma unroll
;                             for (int n = 0; n < 2; ++n) { const f32x4 gv = *(const f32x4*)(g + 32 * bj + 8 * fq + 4 * n);
; #pragma unroll
;                                 for (int j = 0; j < 4; ++j) o[4 * n + j] = v[bj][n][j] * hn * gv[j]; }
;                             st16(dst + (size_t)row * 512 + head * 64 + 32 * bj + 8 * fq, o);
;                         }
;                         asm volatile("" ::: "memory");
;                     }
	v_pk_mul_f32 v[118:119], v[190:191], v[118:119]
	v_pk_mul_f32 v[120:121], v[192:193], v[120:121]
	v_cvt_pk_bf16_f32 v114, v114, v115
	v_cvt_pk_bf16_f32 v115, v116, v117
	v_cvt_pk_bf16_f32 v116, v118, v119
	v_cvt_pk_bf16_f32 v117, v120, v121
	global_store_dwordx4 v[200:201], v[114:117], off
	s_nop 1
	v_pk_mul_f32 v[74:75], v[178:179], v[74:75] op_sel_hi:[0,1]
	v_pk_mul_f32 v[72:73], v[178:179], v[72:73] op_sel_hi:[0,1]
	v_pk_mul_f32 v[62:63], v[176:177], v[62:63] op_sel_hi:[0,1]
	v_pk_mul_f32 v[60:61], v[176:177], v[60:61] op_sel_hi:[0,1]
	v_pk_mul_f32 v[58:59], v[176:177], v[58:59] op_sel_hi:[0,1]
	v_pk_mul_f32 v[56:57], v[176:177], v[56:57] op_sel_hi:[0,1]
	v_pk_mul_f32 v[46:47], v[174:175], v[46:47] op_sel_hi:[0,1]
	v_pk_mul_f32 v[44:45], v[174:175], v[44:45] op_sel_hi:[0,1]
	v_pk_mul_f32 v[42:43], v[174:175], v[42:43] op_sel_hi:[0,1]
	v_pk_mul_f32 v[40:41], v[174:175], v[40:41] op_sel_hi:[0,1]
	v_pk_mul_f32 v[30:31], v[172:173], v[30:31] op_sel_hi:[0,1]
	v_pk_mul_f32 v[28:29], v[172:173], v[28:29] op_sel_hi:[0,1]
	v_pk_mul_f32 v[26:27], v[172:173], v[26:27] op_sel_hi:[0,1]
	v_pk_mul_f32 v[24:25], v[172:173], v[24:25] op_sel_hi:[0,1]
	v_pk_mul_f32 v[14:15], v[170:171], v[14:15] op_sel_hi:[0,1]
	v_pk_mul_f32 v[12:13], v[170:171], v[12:13] op_sel_hi:[0,1]
	v_pk_mul_f32 v[10:11], v[170:171], v[10:11] op_sel_hi:[0,1]
	v_pk_mul_f32 v[8:9], v[170:171], v[8:9] op_sel_hi:[0,1]
	v_pk_mul_f32 v[114:115], v[216:217], v[122:123]
	v_pk_mul_f32 v[116:117], v[218:219], v[124:125]
	v_pk_mul_f32 v[118:119], v[220:221], v[126:127]
	v_pk_mul_f32 v[120:121], v[222:223], v[184:185]
	v_cvt_pk_bf16_f32 v114, v114, v115
	v_cvt_pk_bf16_f32 v115, v116, v117
	v_cvt_pk_bf16_f32 v116, v118, v119
	v_cvt_pk_bf16_f32 v117, v120, v121
	global_store_dwordx4 v[200:201], v[114:117], off offset:64
	v_pk_mul_f32 v[122:123], v[182:183], v[102:103] op_sel_hi:[0,1]
	v_pk_mul_f32 v[124:125], v[182:183], v[100:101] op_sel_hi:[0,1]
	v_pk_mul_f32 v[126:127], v[182:183], v[98:99] op_sel_hi:[0,1]
	v_pk_mul_f32 v[182:183], v[182:183], v[96:97] op_sel_hi:[0,1]
	v_pk_mul_f32 v[96:97], v[110:111], v[110:111]
	v_pk_mul_f32 v[98:99], v[108:109], v[108:109]
	v_pk_mul_f32 v[100:101], v[106:107], v[106:107]
	v_pk_mul_f32 v[102:103], v[104:105], v[104:105]
	v_pk_mov_b32 v[186:187], v[98:99], v[96:97] op_sel:[1,0]
	v_mov_b32_e32 v99, v97
	v_pk_mov_b32 v[96:97], v[102:103], v[100:101] op_sel:[1,0]
	v_mov_b32_e32 v103, v101
	v_mul_f32_e32 v156, v124, v124
	v_mul_f32_e32 v184, v122, v122
	v_pk_add_f32 v[98:99], v[186:187], v[98:99]
	v_pk_add_f32 v[96:97], v[96:97], v[102:103]
	v_pk_fma_f32 v[100:101], v[124:125], v[124:125], v[156:157] op_sel_hi:[1,1,0]
	v_pk_fma_f32 v[184:185], v[122:123], v[122:123], v[184:185] op_sel_hi:[1,1,0]
	v_pk_add_f32 v[98:99], v[98:99], v[98:99] op_sel_hi:[0,1]
	v_pk_add_f32 v[96:97], v[96:97], v[96:97] op_sel_hi:[0,1]
	v_mul_f32_e32 v100, v182, v182
	v_mul_f32_e32 v184, v183, v183
	v_mul_f32_e32 v98, v126, v126
	v_mul_f32_e32 v96, v127, v127
	v_pk_add_f32 v[100:101], v[100:101], v[184:185]
	v_pk_add_f32 v[96:97], v[98:99], v[96:97]
	s_nop 0
	v_pk_add_f32 v[96:97], v[100:101], v[96:97]
	s_nop 0
	v_add_f32_e32 v97, v96, v97
	ds_swizzle_b32 v98, v97 offset:swizzle(SWAP,16)
	v_add_u32_e32 v96, s23, v143
	s_waitcnt lgkmcnt(0)
	v_add_f32_e32 v97, v97, v98
	v_mov_b32_e32 v98, v97
	v_mov_b32_e32 v99, v97
	s_nop 1
	v_permlane32_swap_b32_e32 v98, v99
	v_cndmask_b32_e32 v98, v98, v99, vcc
	v_add_f32_e32 v97, v97, v98
	v_fmamk_f32 v97, v97, 0x3c800000, v212
	v_rsq_f32_e32 v98, v97
	v_ashrrev_i32_e32 v97, 31, v96
	v_lshlrev_b64 v[96:97], 10, v[96:97]
	v_lshl_add_u64 v[184:185], v[112:113], 0, v[96:97]
	v_mul_f32_e32 v156, v173, v98
	v_pk_mul_f32 v[96:97], v[108:109], v[156:157] op_sel_hi:[1,0]
	v_pk_mul_f32 v[98:99], v[110:111], v[156:157] op_sel_hi:[1,0]
	v_pk_mul_f32 v[100:101], v[104:105], v[156:157] op_sel_hi:[1,0]
	v_pk_mul_f32 v[102:103], v[106:107], v[156:157] op_sel_hi:[1,0]
	v_pk_mul_f32 v[104:105], v[124:125], v[156:157] op_sel_hi:[1,0]
	v_pk_mul_f32 v[106:107], v[122:123], v[156:157] op_sel_hi:[1,0]
	v_pk_mul_f32 v[108:109], v[182:183], v[156:157] op_sel_hi:[1,0]
	v_pk_mul_f32 v[110:111], v[126:127], v[156:157] op_sel_hi:[1,0]
	s_waitcnt vmcnt(1)
	v_pk_mul_f32 v[96:97], v[224:225], v[96:97]
	v_pk_mul_f32 v[98:99], v[226:227], v[98:99]
	s_waitcnt vmcnt(0)
	v_pk_mul_f32 v[100:101], v[228:229], v[100:101]
	v_pk_mul_f32 v[102:103], v[230:231], v[102:103]
	v_cvt_pk_bf16_f32 v96, v96, v97
	v_cvt_pk_bf16_f32 v97, v98, v99
	v_cvt_pk_bf16_f32 v98, v100, v101
	v_cvt_pk_bf16_f32 v99, v102, v103
	global_store_dwordx4 v[184:185], v[96:99], off
	s_nop 1
	v_pk_mul_f32 v[96:97], v[216:217], v[104:105]
	v_pk_mul_f32 v[98:99], v[218:219], v[106:107]
	v_pk_mul_f32 v[100:101], v[220:221], v[108:109]
	v_pk_mul_f32 v[102:103], v[222:223], v[110:111]
	v_cvt_pk_bf16_f32 v96, v96, v97
	v_cvt_pk_bf16_f32 v97, v98, v99
	v_cvt_pk_bf16_f32 v98, v100, v101
	v_cvt_pk_bf16_f32 v99, v102, v103
	global_store_dwordx4 v[184:185], v[96:99], off offset:64
	v_pk_mul_f32 v[104:105], v[180:181], v[86:87] op_sel_hi:[0,1]
	v_pk_mul_f32 v[106:107], v[180:181], v[84:85] op_sel_hi:[0,1]
	v_pk_mul_f32 v[108:109], v[180:181], v[82:83] op_sel_hi:[0,1]
	v_pk_mul_f32 v[110:111], v[180:181], v[80:81] op_sel_hi:[0,1]
	v_pk_mul_f32 v[80:81], v[94:95], v[94:95]
	v_pk_mul_f32 v[82:83], v[92:93], v[92:93]
	v_pk_mul_f32 v[84:85], v[90:91], v[90:91]
	v_pk_mul_f32 v[86:87], v[88:89], v[88:89]
	v_pk_mov_b32 v[118:119], v[82:83], v[80:81] op_sel:[1,0]
	v_mov_b32_e32 v83, v81
	v_pk_mov_b32 v[80:81], v[86:87], v[84:85] op_sel:[1,0]
	v_mov_b32_e32 v87, v85
	v_mul_f32_e32 v114, v106, v106
	v_mul_f32_e32 v116, v104, v104
	v_pk_add_f32 v[82:83], v[118:119], v[82:83]
	v_pk_add_f32 v[80:81], v[80:81], v[86:87]
	v_pk_fma_f32 v[84:85], v[106:107], v[106:107], v[114:115] op_sel_hi:[1,1,0]
	v_pk_fma_f32 v[114:115], v[104:105], v[104:105], v[116:117] op_sel_hi:[1,1,0]
	v_pk_add_f32 v[82:83], v[82:83], v[82:83] op_sel_hi:[0,1]
	v_pk_add_f32 v[80:81], v[80:81], v[80:81] op_sel_hi:[0,1]
	v_mul_f32_e32 v84, v110, v110
	v_mul_f32_e32 v114, v111, v111
	v_mul_f32_e32 v82, v108, v108
	v_mul_f32_e32 v80, v109, v109
	v_pk_add_f32 v[84:85], v[84:85], v[114:115]
	v_pk_add_f32 v[80:81], v[82:83], v[80:81]
	s_nop 0
	v_pk_add_f32 v[80:81], v[84:85], v[80:81]
	s_nop 0
	v_add_f32_e32 v81, v80, v81
	ds_swizzle_b32 v82, v81 offset:swizzle(SWAP,16)
	v_add_u32_e32 v80, s23, v145
	s_waitcnt lgkmcnt(0)
;     __device__ __forceinline__ void operator()(const Acc& acc, const Unit& u, int wr, int wc, int fr, int fq) const {
;     ...
;             if (pn < 4) {
;                 const float* g = (pn < 2) ? qg : kg; bf16_t* dst = (pn < 2) ? Q : Kb;
;                 const float post = (pn < 2) ? 0.125f * LOG2E : 1.0f;
;                 const int head = 4 * (pn & 1) + wc;
; #pragma unroll
;                 for (int ai = 0; ai < 2; ++ai)
; #pragma unroll
;                     for (int m = 0; m < 4; ++m) {
;                         const int row = u.pm * 256 + ai * 128 + wr * 64 + m * 16 + fr;
;                         const float rs = rsv[ai][m];
;                         f32x4 v[2][2]; float ss = 0.f;
; #pragma unroll
;                         for (int bj = 0; bj < 2; ++bj)
; #pragma unroll
;                             for (int n = 0; n < 2; ++n) { v[bj][n] = acc[ai][bj][m][n] * rs; const f32x4 x = v[bj][n]; ss += (x[0] * x[0] + x[1] * x[1]) + (x[2] * x[2] + x[3] * x[3]); }
;                         ss += xshfl<16>(ss); ss += xshfl<32>(ss);
;                         const float hn = __builtin_amdgcn_rsqf(ss * (1.f / 64.f) + EPS) * post;
; #pragma unroll
;                         for (int bj = 0; bj < 2; ++bj) {
;                             float o[8];
; #pragma unroll
;                             for (int n = 0; n < 2; ++n) { const f32x4 gv = *(const f32x4*)(g + 32 * bj + 8 * fq + 4 * n);
; #pragma unroll
;                                 for (int j = 0; j < 4; ++j) o[4 * n + j] = v[bj][n][j] * hn * gv[j]; }
;                             st16(dst + (size_t)row * 512 + head * 64 + 32 * bj + 8 * fq, o);
;                         }
;                         asm volatile("" ::: "memory");
;                     }
	v_add_f32_e32 v81, v81, v82
	v_mov_b32_e32 v82, v81
	v_mov_b32_e32 v83, v81
	s_nop 1
	v_permlane32_swap_b32_e32 v82, v83
	v_cndmask_b32_e32 v82, v82, v83, vcc
	v_add_f32_e32 v81, v81, v82
	v_fmamk_f32 v81, v81, 0x3c800000, v212
	v_rsq_f32_e32 v82, v81
	v_ashrrev_i32_e32 v81, 31, v80
	v_lshlrev_b64 v[80:81], 10, v[80:81]
	v_lshl_add_u64 v[114:115], v[112:113], 0, v[80:81]
	v_mul_f32_e32 v116, v173, v82
	v_pk_mul_f32 v[80:81], v[92:93], v[116:117] op_sel_hi:[1,0]
	v_pk_mul_f32 v[82:83], v[94:95], v[116:117] op_sel_hi:[1,0]
	v_pk_mul_f32 v[84:85], v[88:89], v[116:117] op_sel_hi:[1,0]
	v_pk_mul_f32 v[86:87], v[90:91], v[116:117] op_sel_hi:[1,0]
	v_pk_mul_f32 v[88:89], v[106:107], v[116:117] op_sel_hi:[1,0]
	v_pk_mul_f32 v[90:91], v[104:105], v[116:117] op_sel_hi:[1,0]
	v_pk_mul_f32 v[92:93], v[110:111], v[116:117] op_sel_hi:[1,0]
	v_pk_mul_f32 v[94:95], v[108:109], v[116:117] op_sel_hi:[1,0]
	s_waitcnt vmcnt(1)
	v_pk_mul_f32 v[80:81], v[224:225], v[80:81]
	v_pk_mul_f32 v[82:83], v[226:227], v[82:83]
	s_waitcnt vmcnt(0)
	v_pk_mul_f32 v[84:85], v[228:229], v[84:85]
	v_pk_mul_f32 v[86:87], v[230:231], v[86:87]
	v_cvt_pk_bf16_f32 v80, v80, v81
	v_cvt_pk_bf16_f32 v81, v82, v83
	v_cvt_pk_bf16_f32 v82, v84, v85
	v_cvt_pk_bf16_f32 v83, v86, v87
	global_store_dwordx4 v[114:115], v[80:83], off
	s_nop 1
	v_pk_mul_f32 v[80:81], v[216:217], v[88:89]
	v_pk_mul_f32 v[82:83], v[218:219], v[90:91]
	v_pk_mul_f32 v[84:85], v[220:221], v[92:93]
	v_pk_mul_f32 v[86:87], v[222:223], v[94:95]
	v_cvt_pk_bf16_f32 v80, v80, v81
	v_cvt_pk_bf16_f32 v81, v82, v83
	v_cvt_pk_bf16_f32 v82, v84, v85
	v_cvt_pk_bf16_f32 v83, v86, v87
	global_store_dwordx4 v[114:115], v[80:83], off offset:64
	v_pk_mul_f32 v[88:89], v[178:179], v[70:71] op_sel_hi:[0,1]
	v_pk_mul_f32 v[90:91], v[178:179], v[68:69] op_sel_hi:[0,1]
	v_pk_mul_f32 v[92:93], v[178:179], v[66:67] op_sel_hi:[0,1]
	v_pk_mul_f32 v[94:95], v[178:179], v[64:65] op_sel_hi:[0,1]
	v_pk_mul_f32 v[64:65], v[78:79], v[78:79]
	v_pk_mul_f32 v[66:67], v[76:77], v[76:77]
	v_pk_mul_f32 v[68:69], v[74:75], v[74:75]
	v_pk_mul_f32 v[70:71], v[72:73], v[72:73]
	v_pk_mov_b32 v[100:101], v[66:67], v[64:65] op_sel:[1,0]
	v_mov_b32_e32 v67, v65
	v_pk_mov_b32 v[64:65], v[70:71], v[68:69] op_sel:[1,0]
	v_mov_b32_e32 v71, v69
	v_mul_f32_e32 v96, v90, v90
	v_mul_f32_e32 v98, v88, v88
	v_pk_add_f32 v[66:67], v[100:101], v[66:67]
	v_pk_add_f32 v[64:65], v[64:65], v[70:71]
	v_pk_fma_f32 v[68:69], v[90:91], v[90:91], v[96:97] op_sel_hi:[1,1,0]
	v_pk_fma_f32 v[96:97], v[88:89], v[88:89], v[98:99] op_sel_hi:[1,1,0]
	v_pk_add_f32 v[66:67], v[66:67], v[66:67] op_sel_hi:[0,1]
	v_pk_add_f32 v[64:65], v[64:65], v[64:65] op_sel_hi:[0,1]
	v_mul_f32_e32 v68, v94, v94
	v_mul_f32_e32 v96, v95, v95
	v_mul_f32_e32 v66, v92, v92
	v_mul_f32_e32 v64, v93, v93
	v_pk_add_f32 v[68:69], v[68:69], v[96:97]
	v_pk_add_f32 v[64:65], v[66:67], v[64:65]
	s_nop 0
	v_pk_add_f32 v[64:65], v[68:69], v[64:65]
	s_nop 0
	v_add_f32_e32 v65, v64, v65
	ds_swizzle_b32 v66, v65 offset:swizzle(SWAP,16)
	v_add_u32_e32 v64, s23, v147
	s_waitcnt lgkmcnt(0)
	v_add_f32_e32 v65, v65, v66
	v_mov_b32_e32 v66, v65
	v_mov_b32_e32 v67, v65
	s_nop 1
	v_permlane32_swap_b32_e32 v66, v67
	v_cndmask_b32_e32 v66, v66, v67, vcc
	v_add_f32_e32 v65, v65, v66
	v_fmamk_f32 v65, v65, 0x3c800000, v212
	v_rsq_f32_e32 v66, v65
	v_ashrrev_i32_e32 v65, 31, v64
	v_lshlrev_b64 v[64:65], 10, v[64:65]
	v_lshl_add_u64 v[96:97], v[112:113], 0, v[64:65]
	v_mul_f32_e32 v98, v173, v66
	v_pk_mul_f32 v[64:65], v[76:77], v[98:99] op_sel_hi:[1,0]
	v_pk_mul_f32 v[66:67], v[78:79], v[98:99] op_sel_hi:[1,0]
	v_pk_mul_f32 v[68:69], v[72:73], v[98:99] op_sel_hi:[1,0]
	v_pk_mul_f32 v[70:71], v[74:75], v[98:99] op_sel_hi:[1,0]
	v_pk_mul_f32 v[72:73], v[90:91], v[98:99] op_sel_hi:[1,0]
	v_pk_mul_f32 v[74:75], v[88:89], v[98:99] op_sel_hi:[1,0]
	v_pk_mul_f32 v[76:77], v[94:95], v[98:99] op_sel_hi:[1,0]
	v_pk_mul_f32 v[78:79], v[92:93], v[98:99] op_sel_hi:[1,0]
	s_waitcnt vmcnt(1)
	v_pk_mul_f32 v[64:65], v[224:225], v[64:65]
	v_pk_mul_f32 v[66:67], v[226:227], v[66:67]
	s_waitcnt vmcnt(0)
	v_pk_mul_f32 v[68:69], v[228:229], v[68:69]
	v_pk_mul_f32 v[70:71], v[230:231], v[70:71]
	v_cvt_pk_bf16_f32 v64, v64, v65
	v_cvt_pk_bf16_f32 v65, v66, v67
	v_cvt_pk_bf16_f32 v66, v68, v69
	v_cvt_pk_bf16_f32 v67, v70, v71
	global_store_dwordx4 v[96:97], v[64:67], off
	s_nop 1
	v_pk_mul_f32 v[64:65], v[216:217], v[72:73]
	v_pk_mul_f32 v[66:67], v[218:219], v[74:75]
	v_pk_mul_f32 v[68:69], v[220:221], v[76:77]
	v_pk_mul_f32 v[70:71], v[222:223], v[78:79]
	v_cvt_pk_bf16_f32 v64, v64, v65
	v_cvt_pk_bf16_f32 v65, v66, v67
	v_cvt_pk_bf16_f32 v66, v68, v69
	v_cvt_pk_bf16_f32 v67, v70, v71
	global_store_dwordx4 v[96:97], v[64:67], off offset:64
	v_pk_mul_f32 v[72:73], v[176:177], v[54:55] op_sel_hi:[0,1]
	v_pk_mul_f32 v[74:75], v[176:177], v[52:53] op_sel_hi:[0,1]
	v_pk_mul_f32 v[76:77], v[176:177], v[50:51] op_sel_hi:[0,1]
	v_pk_mul_f32 v[78:79], v[176:177], v[48:49] op_sel_hi:[0,1]
	v_pk_mul_f32 v[48:49], v[62:63], v[62:63]
	v_pk_mul_f32 v[50:51], v[60:61], v[60:61]
	v_pk_mul_f32 v[52:53], v[58:59], v[58:59]
	v_pk_mul_f32 v[54:55], v[56:57], v[56:57]
	v_pk_mov_b32 v[84:85], v[50:51], v[48:49] op_sel:[1,0]
	v_mov_b32_e32 v51, v49
	v_pk_mov_b32 v[48:49], v[54:55], v[52:53] op_sel:[1,0]
	v_mov_b32_e32 v55, v53
	v_mul_f32_e32 v80, v74, v74
	v_mul_f32_e32 v82, v72, v72
	v_pk_add_f32 v[50:51], v[84:85], v[50:51]
	v_pk_add_f32 v[48:49], v[48:49], v[54:55]
	v_pk_fma_f32 v[52:53], v[74:75], v[74:75], v[80:81] op_sel_hi:[1,1,0]
	v_pk_fma_f32 v[80:81], v[72:73], v[72:73], v[82:83] op_sel_hi:[1,1,0]
	v_pk_add_f32 v[50:51], v[50:51], v[50:51] op_sel_hi:[0,1]
	v_pk_add_f32 v[48:49], v[48:49], v[48:49] op_sel_hi:[0,1]
	v_mul_f32_e32 v52, v78, v78
	v_mul_f32_e32 v80, v79, v79
	v_mul_f32_e32 v50, v76, v76
	v_mul_f32_e32 v48, v77, v77
	v_pk_add_f32 v[52:53], v[52:53], v[80:81]
	v_pk_add_f32 v[48:49], v[50:51], v[48:49]
	s_nop 0
	v_pk_add_f32 v[48:49], v[52:53], v[48:49]
	s_nop 0
	v_add_f32_e32 v49, v48, v49
	ds_swizzle_b32 v50, v49 offset:swizzle(SWAP,16)
	v_add_u32_e32 v48, s23, v149
	s_waitcnt lgkmcnt(0)
;     __device__ __forceinline__ void operator()(const Acc& acc, const Unit& u, int wr, int wc, int fr, int fq) const {
;     ...
;             if (pn < 4) {
;                 const float* g = (pn < 2) ? qg : kg; bf16_t* dst = (pn < 2) ? Q : Kb;
;                 const float post = (pn < 2) ? 0.125f * LOG2E : 1.0f;
;                 const int head = 4 * (pn & 1) + wc;
; #pragma unroll
;                 for (int ai = 0; ai < 2; ++ai)
; #pragma unroll
;                     for (int m = 0; m < 4; ++m) {
;                         const int row = u.pm * 256 + ai * 128 + wr * 64 + m * 16 + fr;
;                         const float rs = rsv[ai][m];
;                         f32x4 v[2][2]; float ss = 0.f;
; #pragma unroll
;                         for (int bj = 0; bj < 2; ++bj)
; #pragma unroll
;                             for (int n = 0; n < 2; ++n) { v[bj][n] = acc[ai][bj][m][n] * rs; const f32x4 x = v[bj][n]; ss += (x[0] * x[0] + x[1] * x[1]) + (x[2] * x[2] + x[3] * x[3]); }
;                         ss += xshfl<16>(ss); ss += xshfl<32>(ss);
;                         const float hn = __builtin_amdgcn_rsqf(ss * (1.f / 64.f) + EPS) * post;
; #pragma unroll
;                         for (int bj = 0; bj < 2; ++bj) {
;                             float o[8];
; #pragma unroll
;                             for (int n = 0; n < 2; ++n) { const f32x4 gv = *(const f32x4*)(g + 32 * bj + 8 * fq + 4 * n);
; #pragma unroll
;                                 for (int j = 0; j < 4; ++j) o[4 * n + j] = v[bj][n][j] * hn * gv[j]; }
;                             st16(dst + (size_t)row * 512 + head * 64 + 32 * bj + 8 * fq, o);
;                         }
;                         asm volatile("" ::: "memory");
;                     }
	v_add_f32_e32 v49, v49, v50
	v_mov_b32_e32 v50, v49
	v_mov_b32_e32 v51, v49
	s_nop 1
	v_permlane32_swap_b32_e32 v50, v51
	v_cndmask_b32_e32 v50, v50, v51, vcc
	v_add_f32_e32 v49, v49, v50
	v_fmamk_f32 v49, v49, 0x3c800000, v212
	v_rsq_f32_e32 v50, v49
	v_ashrrev_i32_e32 v49, 31, v48
	v_lshlrev_b64 v[48:49], 10, v[48:49]
	v_lshl_add_u64 v[80:81], v[112:113], 0, v[48:49]
	v_mul_f32_e32 v82, v173, v50
	v_pk_mul_f32 v[48:49], v[60:61], v[82:83] op_sel_hi:[1,0]
	v_pk_mul_f32 v[50:51], v[62:63], v[82:83] op_sel_hi:[1,0]
	v_pk_mul_f32 v[52:53], v[56:57], v[82:83] op_sel_hi:[1,0]
	v_pk_mul_f32 v[54:55], v[58:59], v[82:83] op_sel_hi:[1,0]
	v_pk_mul_f32 v[56:57], v[74:75], v[82:83] op_sel_hi:[1,0]
	v_pk_mul_f32 v[58:59], v[72:73], v[82:83] op_sel_hi:[1,0]
	v_pk_mul_f32 v[60:61], v[78:79], v[82:83] op_sel_hi:[1,0]
	v_pk_mul_f32 v[62:63], v[76:77], v[82:83] op_sel_hi:[1,0]
	s_waitcnt vmcnt(1)
	v_pk_mul_f32 v[48:49], v[224:225], v[48:49]
	v_pk_mul_f32 v[50:51], v[226:227], v[50:51]
	s_waitcnt vmcnt(0)
	v_pk_mul_f32 v[52:53], v[228:229], v[52:53]
	v_pk_mul_f32 v[54:55], v[230:231], v[54:55]
	v_cvt_pk_bf16_f32 v48, v48, v49
	v_cvt_pk_bf16_f32 v49, v50, v51
	v_cvt_pk_bf16_f32 v50, v52, v53
	v_cvt_pk_bf16_f32 v51, v54, v55
	global_store_dwordx4 v[80:81], v[48:51], off
	s_nop 1
	v_pk_mul_f32 v[48:49], v[216:217], v[56:57]
	v_pk_mul_f32 v[50:51], v[218:219], v[58:59]
	v_pk_mul_f32 v[52:53], v[220:221], v[60:61]
	v_pk_mul_f32 v[54:55], v[222:223], v[62:63]
	v_cvt_pk_bf16_f32 v48, v48, v49
	v_cvt_pk_bf16_f32 v49, v50, v51
	v_cvt_pk_bf16_f32 v50, v52, v53
	v_cvt_pk_bf16_f32 v51, v54, v55
	global_store_dwordx4 v[80:81], v[48:51], off offset:64
	v_pk_mul_f32 v[56:57], v[174:175], v[38:39] op_sel_hi:[0,1]
	v_pk_mul_f32 v[58:59], v[174:175], v[36:37] op_sel_hi:[0,1]
	v_pk_mul_f32 v[60:61], v[174:175], v[34:35] op_sel_hi:[0,1]
	v_pk_mul_f32 v[62:63], v[174:175], v[32:33] op_sel_hi:[0,1]
	v_pk_mul_f32 v[32:33], v[46:47], v[46:47]
	v_pk_mul_f32 v[34:35], v[44:45], v[44:45]
	v_pk_mul_f32 v[36:37], v[42:43], v[42:43]
	v_pk_mul_f32 v[38:39], v[40:41], v[40:41]
	v_pk_mov_b32 v[68:69], v[34:35], v[32:33] op_sel:[1,0]
	v_mov_b32_e32 v35, v33
	v_pk_mov_b32 v[32:33], v[38:39], v[36:37] op_sel:[1,0]
	v_mov_b32_e32 v39, v37
	v_mul_f32_e32 v64, v58, v58
	v_mul_f32_e32 v66, v56, v56
	v_pk_add_f32 v[34:35], v[68:69], v[34:35]
	v_pk_add_f32 v[32:33], v[32:33], v[38:39]
	v_pk_fma_f32 v[36:37], v[58:59], v[58:59], v[64:65] op_sel_hi:[1,1,0]
	v_pk_fma_f32 v[64:65], v[56:57], v[56:57], v[66:67] op_sel_hi:[1,1,0]
	v_pk_add_f32 v[34:35], v[34:35], v[34:35] op_sel_hi:[0,1]
	v_pk_add_f32 v[32:33], v[32:33], v[32:33] op_sel_hi:[0,1]
	v_mul_f32_e32 v36, v62, v62
	v_mul_f32_e32 v64, v63, v63
	v_mul_f32_e32 v34, v60, v60
	v_mul_f32_e32 v32, v61, v61
	v_pk_add_f32 v[36:37], v[36:37], v[64:65]
	v_pk_add_f32 v[32:33], v[34:35], v[32:33]
	s_nop 0
	v_pk_add_f32 v[32:33], v[36:37], v[32:33]
	s_nop 0
	v_add_f32_e32 v33, v32, v33
	ds_swizzle_b32 v34, v33 offset:swizzle(SWAP,16)
	v_add_u32_e32 v32, s23, v151
	s_waitcnt lgkmcnt(0)
	v_add_f32_e32 v33, v33, v34
	v_mov_b32_e32 v34, v33
	v_mov_b32_e32 v35, v33
	s_nop 1
	v_permlane32_swap_b32_e32 v34, v35
	v_cndmask_b32_e32 v34, v34, v35, vcc
	v_add_f32_e32 v33, v33, v34
	v_fmamk_f32 v33, v33, 0x3c800000, v212
	v_rsq_f32_e32 v34, v33
	v_ashrrev_i32_e32 v33, 31, v32
	v_lshlrev_b64 v[32:33], 10, v[32:33]
	v_lshl_add_u64 v[64:65], v[112:113], 0, v[32:33]
	v_mul_f32_e32 v66, v173, v34
	v_pk_mul_f32 v[32:33], v[44:45], v[66:67] op_sel_hi:[1,0]
	v_pk_mul_f32 v[34:35], v[46:47], v[66:67] op_sel_hi:[1,0]
	v_pk_mul_f32 v[36:37], v[40:41], v[66:67] op_sel_hi:[1,0]
	v_pk_mul_f32 v[38:39], v[42:43], v[66:67] op_sel_hi:[1,0]
	v_pk_mul_f32 v[40:41], v[58:59], v[66:67] op_sel_hi:[1,0]
	v_pk_mul_f32 v[42:43], v[56:57], v[66:67] op_sel_hi:[1,0]
	v_pk_mul_f32 v[44:45], v[62:63], v[66:67] op_sel_hi:[1,0]
	v_pk_mul_f32 v[46:47], v[60:61], v[66:67] op_sel_hi:[1,0]
	s_waitcnt vmcnt(1)
	v_pk_mul_f32 v[32:33], v[224:225], v[32:33]
	v_pk_mul_f32 v[34:35], v[226:227], v[34:35]
	s_waitcnt vmcnt(0)
	v_pk_mul_f32 v[36:37], v[228:229], v[36:37]
	v_pk_mul_f32 v[38:39], v[230:231], v[38:39]
	v_cvt_pk_bf16_f32 v32, v32, v33
	v_cvt_pk_bf16_f32 v33, v34, v35
	v_cvt_pk_bf16_f32 v34, v36, v37
	v_cvt_pk_bf16_f32 v35, v38, v39
	global_store_dwordx4 v[64:65], v[32:35], off
	s_nop 1
	v_pk_mul_f32 v[32:33], v[216:217], v[40:41]
	v_pk_mul_f32 v[34:35], v[218:219], v[42:43]
	v_pk_mul_f32 v[36:37], v[220:221], v[44:45]
	v_pk_mul_f32 v[38:39], v[222:223], v[46:47]
	v_cvt_pk_bf16_f32 v32, v32, v33
	v_cvt_pk_bf16_f32 v33, v34, v35
	v_cvt_pk_bf16_f32 v34, v36, v37
	v_cvt_pk_bf16_f32 v35, v38, v39
	global_store_dwordx4 v[64:65], v[32:35], off offset:64
	v_pk_mul_f32 v[40:41], v[172:173], v[22:23] op_sel_hi:[0,1]
	v_pk_mul_f32 v[42:43], v[172:173], v[20:21] op_sel_hi:[0,1]
	v_pk_mul_f32 v[44:45], v[172:173], v[18:19] op_sel_hi:[0,1]
	v_pk_mul_f32 v[46:47], v[172:173], v[16:17] op_sel_hi:[0,1]
	v_pk_mul_f32 v[16:17], v[30:31], v[30:31]
	v_pk_mul_f32 v[18:19], v[28:29], v[28:29]
	v_pk_mul_f32 v[20:21], v[26:27], v[26:27]
	v_pk_mul_f32 v[22:23], v[24:25], v[24:25]
	v_pk_mov_b32 v[52:53], v[18:19], v[16:17] op_sel:[1,0]
	v_mov_b32_e32 v19, v17
	v_pk_mov_b32 v[16:17], v[22:23], v[20:21] op_sel:[1,0]
	v_mov_b32_e32 v23, v21
	v_mul_f32_e32 v48, v42, v42
	v_mul_f32_e32 v50, v40, v40
	v_pk_add_f32 v[18:19], v[52:53], v[18:19]
	v_pk_add_f32 v[16:17], v[16:17], v[22:23]
	v_pk_fma_f32 v[20:21], v[42:43], v[42:43], v[48:49] op_sel_hi:[1,1,0]
	v_pk_fma_f32 v[48:49], v[40:41], v[40:41], v[50:51] op_sel_hi:[1,1,0]
	v_pk_add_f32 v[18:19], v[18:19], v[18:19] op_sel_hi:[0,1]
	v_pk_add_f32 v[16:17], v[16:17], v[16:17] op_sel_hi:[0,1]
	v_mul_f32_e32 v20, v46, v46
	v_mul_f32_e32 v48, v47, v47
	v_mul_f32_e32 v18, v44, v44
	v_mul_f32_e32 v16, v45, v45
	v_pk_add_f32 v[20:21], v[20:21], v[48:49]
	v_pk_add_f32 v[16:17], v[18:19], v[16:17]
	s_nop 0
	v_pk_add_f32 v[16:17], v[20:21], v[16:17]
	s_nop 0
	v_add_f32_e32 v17, v16, v17
	ds_swizzle_b32 v18, v17 offset:swizzle(SWAP,16)
	v_add_u32_e32 v16, s23, v153
	s_waitcnt lgkmcnt(0)
;     __device__ __forceinline__ void operator()(const Acc& acc, const Unit& u, int wr, int wc, int fr, int fq) const {
;     ...
;             if (pn < 4) {
;                 const float* g = (pn < 2) ? qg : kg; bf16_t* dst = (pn < 2) ? Q : Kb;
;                 const float post = (pn < 2) ? 0.125f * LOG2E : 1.0f;
;                 const int head = 4 * (pn & 1) + wc;
; #pragma unroll
;                 for (int ai = 0; ai < 2; ++ai)
; #pragma unroll
;                     for (int m = 0; m < 4; ++m) {
;                         const int row = u.pm * 256 + ai * 128 + wr * 64 + m * 16 + fr;
;                         const float rs = rsv[ai][m];
;                         f32x4 v[2][2]; float ss = 0.f;
; #pragma unroll
;                         for (int bj = 0; bj < 2; ++bj)
; #pragma unroll
;                             for (int n = 0; n < 2; ++n) { v[bj][n] = acc[ai][bj][m][n] * rs; const f32x4 x = v[bj][n]; ss += (x[0] * x[0] + x[1] * x[1]) + (x[2] * x[2] + x[3] * x[3]); }
;                         ss += xshfl<16>(ss); ss += xshfl<32>(ss);
;                         const float hn = __builtin_amdgcn_rsqf(ss * (1.f / 64.f) + EPS) * post;
; #pragma unroll
;                         for (int bj = 0; bj < 2; ++bj) {
;                             float o[8];
; #pragma unroll
;                             for (int n = 0; n < 2; ++n) { const f32x4 gv = *(const f32x4*)(g + 32 * bj + 8 * fq + 4 * n);
; #pragma unroll
;                                 for (int j = 0; j < 4; ++j) o[4 * n + j] = v[bj][n][j] * hn * gv[j]; }
;                             st16(dst + (size_t)row * 512 + head * 64 + 32 * bj + 8 * fq, o);
;                         }
;                         asm volatile("" ::: "memory");
;                     }
	v_add_f32_e32 v17, v17, v18
	v_mov_b32_e32 v18, v17
	v_mov_b32_e32 v19, v17
	s_nop 1
	v_permlane32_swap_b32_e32 v18, v19
	v_cndmask_b32_e32 v18, v18, v19, vcc
	v_add_f32_e32 v17, v17, v18
	v_fmamk_f32 v17, v17, 0x3c800000, v212
	v_rsq_f32_e32 v18, v17
	v_ashrrev_i32_e32 v17, 31, v16
	v_lshlrev_b64 v[16:17], 10, v[16:17]
	v_lshl_add_u64 v[48:49], v[112:113], 0, v[16:17]
	v_mul_f32_e32 v50, v173, v18
	v_pk_mul_f32 v[16:17], v[28:29], v[50:51] op_sel_hi:[1,0]
	v_pk_mul_f32 v[18:19], v[30:31], v[50:51] op_sel_hi:[1,0]
	v_pk_mul_f32 v[20:21], v[24:25], v[50:51] op_sel_hi:[1,0]
	v_pk_mul_f32 v[22:23], v[26:27], v[50:51] op_sel_hi:[1,0]
	v_pk_mul_f32 v[24:25], v[42:43], v[50:51] op_sel_hi:[1,0]
	v_pk_mul_f32 v[26:27], v[40:41], v[50:51] op_sel_hi:[1,0]
	v_pk_mul_f32 v[28:29], v[46:47], v[50:51] op_sel_hi:[1,0]
	v_pk_mul_f32 v[30:31], v[44:45], v[50:51] op_sel_hi:[1,0]
	s_waitcnt vmcnt(1)
	v_pk_mul_f32 v[16:17], v[224:225], v[16:17]
	v_pk_mul_f32 v[18:19], v[226:227], v[18:19]
	s_waitcnt vmcnt(0)
	v_pk_mul_f32 v[20:21], v[228:229], v[20:21]
	v_pk_mul_f32 v[22:23], v[230:231], v[22:23]
	v_cvt_pk_bf16_f32 v16, v16, v17
	v_cvt_pk_bf16_f32 v17, v18, v19
	v_cvt_pk_bf16_f32 v18, v20, v21
	v_cvt_pk_bf16_f32 v19, v22, v23
	global_store_dwordx4 v[48:49], v[16:19], off
	s_nop 1
	v_pk_mul_f32 v[16:17], v[216:217], v[24:25]
	v_pk_mul_f32 v[18:19], v[218:219], v[26:27]
	v_pk_mul_f32 v[20:21], v[220:221], v[28:29]
	v_pk_mul_f32 v[22:23], v[222:223], v[30:31]
	v_cvt_pk_bf16_f32 v16, v16, v17
	v_cvt_pk_bf16_f32 v17, v18, v19
	v_cvt_pk_bf16_f32 v18, v20, v21
	v_cvt_pk_bf16_f32 v19, v22, v23
	global_store_dwordx4 v[48:49], v[16:19], off offset:64
	v_pk_mul_f32 v[24:25], v[170:171], v[6:7] op_sel_hi:[0,1]
	v_pk_mul_f32 v[26:27], v[170:171], v[4:5] op_sel_hi:[0,1]
	v_pk_mul_f32 v[28:29], v[170:171], v[2:3] op_sel_hi:[0,1]
	v_pk_mul_f32 v[30:31], v[170:171], v[0:1] op_sel_hi:[0,1]
	v_pk_mul_f32 v[0:1], v[14:15], v[14:15]
	v_pk_mul_f32 v[2:3], v[12:13], v[12:13]
	v_pk_mul_f32 v[4:5], v[10:11], v[10:11]
	v_pk_mul_f32 v[6:7], v[8:9], v[8:9]
	v_pk_mov_b32 v[36:37], v[2:3], v[0:1] op_sel:[1,0]
	v_mov_b32_e32 v3, v1
	v_pk_mov_b32 v[0:1], v[6:7], v[4:5] op_sel:[1,0]
	v_mov_b32_e32 v7, v5
	v_mul_f32_e32 v32, v26, v26
	v_mul_f32_e32 v34, v24, v24
	v_pk_add_f32 v[2:3], v[36:37], v[2:3]
	v_pk_add_f32 v[0:1], v[0:1], v[6:7]
	v_pk_fma_f32 v[4:5], v[26:27], v[26:27], v[32:33] op_sel_hi:[1,1,0]
	v_pk_fma_f32 v[32:33], v[24:25], v[24:25], v[34:35] op_sel_hi:[1,1,0]
	v_pk_add_f32 v[2:3], v[2:3], v[2:3] op_sel_hi:[0,1]
	v_pk_add_f32 v[0:1], v[0:1], v[0:1] op_sel_hi:[0,1]
	v_mul_f32_e32 v4, v30, v30
	v_mul_f32_e32 v32, v31, v31
	v_mul_f32_e32 v2, v28, v28
	v_mul_f32_e32 v0, v29, v29
	v_pk_add_f32 v[4:5], v[4:5], v[32:33]
	v_pk_add_f32 v[0:1], v[2:3], v[0:1]
	s_nop 0
	v_pk_add_f32 v[0:1], v[4:5], v[0:1]
	s_nop 0
	v_add_f32_e32 v1, v0, v1
	ds_swizzle_b32 v2, v1 offset:swizzle(SWAP,16)
	v_add_u32_e32 v0, s23, v155
	s_waitcnt lgkmcnt(0)
	v_add_f32_e32 v1, v1, v2
	v_mov_b32_e32 v2, v1
	v_mov_b32_e32 v3, v1
	s_nop 1
	v_permlane32_swap_b32_e32 v2, v3
	v_cndmask_b32_e32 v2, v2, v3, vcc
	v_add_f32_e32 v1, v1, v2
	v_fmamk_f32 v1, v1, 0x3c800000, v212
	v_rsq_f32_e32 v2, v1
	v_ashrrev_i32_e32 v1, 31, v0
	v_lshlrev_b64 v[0:1], 10, v[0:1]
	v_lshl_add_u64 v[32:33], v[112:113], 0, v[0:1]
	v_mul_f32_e32 v34, v173, v2
	v_pk_mul_f32 v[0:1], v[12:13], v[34:35] op_sel_hi:[1,0]
	v_pk_mul_f32 v[2:3], v[14:15], v[34:35] op_sel_hi:[1,0]
	v_pk_mul_f32 v[4:5], v[8:9], v[34:35] op_sel_hi:[1,0]
	v_pk_mul_f32 v[6:7], v[10:11], v[34:35] op_sel_hi:[1,0]
	v_pk_mul_f32 v[8:9], v[26:27], v[34:35] op_sel_hi:[1,0]
	v_pk_mul_f32 v[10:11], v[24:25], v[34:35] op_sel_hi:[1,0]
	v_pk_mul_f32 v[12:13], v[30:31], v[34:35] op_sel_hi:[1,0]
	v_pk_mul_f32 v[14:15], v[28:29], v[34:35] op_sel_hi:[1,0]
	s_waitcnt vmcnt(1)
	v_pk_mul_f32 v[0:1], v[224:225], v[0:1]
	v_pk_mul_f32 v[2:3], v[226:227], v[2:3]
	s_waitcnt vmcnt(0)
	v_pk_mul_f32 v[4:5], v[228:229], v[4:5]
	v_pk_mul_f32 v[6:7], v[230:231], v[6:7]
	v_cvt_pk_bf16_f32 v0, v0, v1
	v_cvt_pk_bf16_f32 v1, v2, v3
	v_cvt_pk_bf16_f32 v2, v4, v5
	v_cvt_pk_bf16_f32 v3, v6, v7
	global_store_dwordx4 v[32:33], v[0:3], off
	s_nop 1
	v_pk_mul_f32 v[0:1], v[216:217], v[8:9]
	v_pk_mul_f32 v[2:3], v[218:219], v[10:11]
	v_pk_mul_f32 v[4:5], v[220:221], v[12:13]
	v_pk_mul_f32 v[6:7], v[222:223], v[14:15]
	v_cvt_pk_bf16_f32 v0, v0, v1
	v_cvt_pk_bf16_f32 v1, v2, v3
	v_cvt_pk_bf16_f32 v2, v4, v5
	v_cvt_pk_bf16_f32 v3, v6, v7
	global_store_dwordx4 v[32:33], v[0:3], off offset:64
